# attention S1 (QK): all 8 K fragment reads issued up front into own quads (on top of hand-scheduled S2, ccdma, trims)
# speedup vs baseline: 1.0264x; 1.0071x over previous
; #define MFMA32(a, b, c) __builtin_amdgcn_mfma_f32_32x32x16_bf16((a), (b), (c), 0, 0, 0)
; #define LOADV(dst, ks_) do { _Pragma("unroll") for (int dvb = 0; dvb < 4; ++dvb) { dst[2 * dvb] = vtr(vp + dvb * 4096 + (ks_) * 1024); dst[2 * dvb + 1] = vtr(vp + dvb * 4096 + (ks_) * 1024 + 512); } } while (0)
; DI void attn_unit(const Params& p, int bh, int qb, char* lds, float lam, int tid, int lane, int wid, const bool build_tab) {
;     ...
;             const lds_cptr kp = (lds_cptr)lds + sc + map * 8192 + hi * 1024 + r32 * 16;
;             bf16x8 kf[8];
; #pragma unroll
;             for (int d0 = 0; d0 < 4; ++d0) {
;                 kf[2 * d0] = *(const __attribute__((address_space(3))) bf16x8*)(kp + d0 * 2048);
;                 kf[2 * d0 + 1] = *(const __attribute__((address_space(3))) bf16x8*)(kp + d0 * 2048 + 512);
;             }
;             f32x16 s0 = cinit, s1 = cinit;
; #pragma unroll
;             for (int d0 = 0; d0 < 4; ++d0) { s0 = MFMA32(kf[2 * d0], qf[d0], s0); s1 = MFMA32(kf[2 * d0 + 1], qf[d0], s1); }
;             LOADV(va, 0);
;             if (t >= 2 * qb - 2) {
;                 const float* tb = tab + (64 * t - (qrow0 + r32) + 256 + 4 * hi);
; #pragma unroll
;                 for (int i = 0; i < 16; ++i) {
;                     s0[i] += tb[(i & 3) + 8 * (i >> 2)];
;                     s1[i] += tb[(i & 3) + 8 * (i >> 2) + 32];
;                 }
;             }
.LBB0_352:
	s_andn2_b64 vcc, exec, s[50:51]
	s_cbranch_vccnz .LBB0_360
	s_add_i32 s50, s84, 0
	s_add_i32 s51, s50, s61
	v_add3_u32 v221, s51, v204, v205
	ds_read_b128 v[128:131], v221
	ds_read_b128 v[222:225], v221 offset:512
	ds_read_b128 v[132:135], v221 offset:2048
	ds_read_b128 v[226:229], v221 offset:2560
	ds_read_b128 v[136:139], v221 offset:4096
	ds_read_b128 v[230:233], v221 offset:4608
	ds_read_b128 v[140:143], v221 offset:6144
	ds_read_b128 v[234:237], v221 offset:6656
	s_cmp_lt_u32 s7, s79
	v_add3_u32 v220, s50, v171, v202
	v_add_u32_e32 v220, v220, v203
	s_waitcnt lgkmcnt(7)
	v_mfma_f32_32x32x16_bf16 v[96:111], v[128:131], v[112:115], v[64:79]
	s_waitcnt lgkmcnt(6)
	v_mfma_f32_32x32x16_bf16 v[80:95], v[222:225], v[112:115], v[64:79]
	s_waitcnt lgkmcnt(5)
	v_mfma_f32_32x32x16_bf16 v[96:111], v[132:135], v[116:119], v[96:111]
	s_waitcnt lgkmcnt(4)
	v_mfma_f32_32x32x16_bf16 v[80:95], v[226:229], v[116:119], v[80:95]
	s_waitcnt lgkmcnt(3)
	v_mfma_f32_32x32x16_bf16 v[96:111], v[136:139], v[120:123], v[96:111]
	s_waitcnt lgkmcnt(2)
	v_mfma_f32_32x32x16_bf16 v[80:95], v[230:233], v[120:123], v[80:95]
	s_waitcnt lgkmcnt(1)
	v_mfma_f32_32x32x16_bf16 v[96:111], v[140:143], v[124:127], v[96:111]
	ds_read_b64_tr_b16 v[140:141], v220 offset:16384
	ds_read_b64_tr_b16 v[142:143], v220 offset:16896
	ds_read_b64_tr_b16 v[136:137], v220 offset:20480
	ds_read_b64_tr_b16 v[138:139], v220 offset:20992
	ds_read_b64_tr_b16 v[132:133], v220 offset:24576
	ds_read_b64_tr_b16 v[134:135], v220 offset:25088
	ds_read_b64_tr_b16 v[128:129], v220 offset:28672
	ds_read_b64_tr_b16 v[130:131], v220 offset:29184
	s_waitcnt lgkmcnt(8)
	v_mfma_f32_32x32x16_bf16 v[80:95], v[234:237], v[124:127], v[80:95]
	s_cbranch_scc1 .LBB0_355
	v_add_u32_e32 v221, s83, v219
	v_add_u32_e32 v222, 0x18600, v221
	v_add_u32_e32 v224, 0x18680, v221
	v_add_u32_e32 v226, 0x18608, v221
	v_add_u32_e32 v228, 0x18688, v221
	v_add_u32_e32 v230, 0x18620, v221
	v_add_u32_e32 v232, 0x186a0, v221
	v_add_u32_e32 v234, 0x18628, v221
	v_add_u32_e32 v236, 0x186a8, v221
	v_add_u32_e32 v238, 0x18640, v221
	v_add_u32_e32 v240, 0x186c0, v221
	v_add_u32_e32 v242, 0x18648, v221
	v_add_u32_e32 v244, 0x186c8, v221
	v_add_u32_e32 v248, 0x18660, v221
	v_add_u32_e32 v250, 0x186e0, v221
	v_add_u32_e32 v246, 0x18668, v221
	ds_read2_b32 v[222:223], v222 offset1:1
	ds_read2_b32 v[224:225], v224 offset1:1
	ds_read2_b32 v[226:227], v226 offset1:1
	ds_read2_b32 v[228:229], v228 offset1:1
	ds_read2_b32 v[230:231], v230 offset1:1
	ds_read2_b32 v[232:233], v232 offset1:1
	ds_read2_b32 v[234:235], v234 offset1:1
	ds_read2_b32 v[236:237], v236 offset1:1
	ds_read2_b32 v[238:239], v238 offset1:1
	ds_read2_b32 v[240:241], v240 offset1:1
	ds_read2_b32 v[242:243], v242 offset1:1
	ds_read2_b32 v[244:245], v244 offset1:1
	ds_read2_b32 v[246:247], v246 offset1:1
	ds_read2_b32 v[248:249], v248 offset1:1
	v_add_u32_e32 v221, 0x186e8, v221
	ds_read2_b32 v[250:251], v250 offset1:1
	ds_read2_b32 v[252:253], v221 offset1:1
	s_waitcnt lgkmcnt(5)
	v_pk_add_f32 v[106:107], v[106:107], v[242:243]
	s_waitcnt lgkmcnt(3)
	v_pk_add_f32 v[110:111], v[110:111], v[246:247]
	s_waitcnt lgkmcnt(2)
	v_pk_add_f32 v[108:109], v[108:109], v[248:249]
	v_pk_add_f32 v[104:105], v[104:105], v[238:239]
	v_pk_add_f32 v[102:103], v[102:103], v[234:235]
	v_pk_add_f32 v[100:101], v[100:101], v[230:231]
	v_pk_add_f32 v[98:99], v[98:99], v[226:227]
	v_pk_add_f32 v[96:97], v[96:97], v[222:223]
	s_waitcnt lgkmcnt(0)
	v_pk_add_f32 v[94:95], v[94:95], v[252:253]
	v_pk_add_f32 v[92:93], v[92:93], v[250:251]
	v_pk_add_f32 v[90:91], v[90:91], v[244:245]
	v_pk_add_f32 v[88:89], v[88:89], v[240:241]
	v_pk_add_f32 v[86:87], v[86:87], v[236:237]
	v_pk_add_f32 v[84:85], v[84:85], v[232:233]
	v_pk_add_f32 v[82:83], v[82:83], v[228:229]
	v_pk_add_f32 v[80:81], v[80:81], v[224:225]

; #define MFMA32(a, b, c) __builtin_amdgcn_mfma_f32_32x32x16_bf16((a), (b), (c), 0, 0, 0)
; #define LOADV(dst, ks_) do { _Pragma("unroll") for (int dvb = 0; dvb < 4; ++dvb) { dst[2 * dvb] = vtr(vp + dvb * 4096 + (ks_) * 1024); dst[2 * dvb + 1] = vtr(vp + dvb * 4096 + (ks_) * 1024 + 512); } } while (0)
; DI void attn_unit(const Params& p, int bh, int qb, char* lds, float lam, int tid, int lane, int wid, const bool build_tab) {
;     ...
;             const lds_cptr kp = (lds_cptr)lds + sc + map * 8192 + hi * 1024 + r32 * 16;
;             bf16x8 kf[8];
; #pragma unroll
;             for (int d0 = 0; d0 < 4; ++d0) {
;                 kf[2 * d0] = *(const __attribute__((address_space(3))) bf16x8*)(kp + d0 * 2048);
;                 kf[2 * d0 + 1] = *(const __attribute__((address_space(3))) bf16x8*)(kp + d0 * 2048 + 512);
;             }
;             f32x16 s0 = cinit, s1 = cinit;
; #pragma unroll
;             for (int d0 = 0; d0 < 4; ++d0) { s0 = MFMA32(kf[2 * d0], qf[d0], s0); s1 = MFMA32(kf[2 * d0 + 1], qf[d0], s1); }
;             LOADV(va, 0);
;             if (t >= 2 * qb - 2) {
;                 const float* tb = tab + (64 * t - (qrow0 + r32) + 256 + 4 * hi);
; #pragma unroll
;                 for (int i = 0; i < 16; ++i) {
;                     s0[i] += tb[(i & 3) + 8 * (i >> 2)];
;                     s1[i] += tb[(i & 3) + 8 * (i >> 2) + 32];
;                 }
;             }
.LBB0_372:
	s_andn2_b64 vcc, exec, s[52:53]
	s_cbranch_vccnz .LBB0_380
	s_add_i32 s52, s70, 0
	s_add_i32 s53, s52, s61
	v_add3_u32 v244, s53, v204, v205
	ds_read_b128 v[128:131], v244
	ds_read_b128 v[178:181], v244 offset:512
	ds_read_b128 v[132:135], v244 offset:2048
	ds_read_b128 v[182:185], v244 offset:2560
	ds_read_b128 v[136:139], v244 offset:4096
	ds_read_b128 v[186:189], v244 offset:4608
	ds_read_b128 v[140:143], v244 offset:6144
	ds_read_b128 v[190:193], v244 offset:6656
	s_cmp_lt_i32 s51, s57
	v_add3_u32 v177, s52, v171, v202
	v_add_u32_e32 v177, v177, v203
	s_waitcnt lgkmcnt(7)
	v_mfma_f32_32x32x16_bf16 v[96:111], v[128:131], v[112:115], v[64:79]
	s_waitcnt lgkmcnt(6)
	v_mfma_f32_32x32x16_bf16 v[80:95], v[178:181], v[112:115], v[64:79]
	s_waitcnt lgkmcnt(5)
	v_mfma_f32_32x32x16_bf16 v[96:111], v[132:135], v[116:119], v[96:111]
	s_waitcnt lgkmcnt(4)
	v_mfma_f32_32x32x16_bf16 v[80:95], v[182:185], v[116:119], v[80:95]
	s_waitcnt lgkmcnt(3)
	v_mfma_f32_32x32x16_bf16 v[96:111], v[136:139], v[120:123], v[96:111]
	s_waitcnt lgkmcnt(2)
	v_mfma_f32_32x32x16_bf16 v[80:95], v[186:189], v[120:123], v[80:95]
	s_waitcnt lgkmcnt(1)
	v_mfma_f32_32x32x16_bf16 v[96:111], v[140:143], v[124:127], v[96:111]
	ds_read_b64_tr_b16 v[140:141], v177 offset:16384
	ds_read_b64_tr_b16 v[142:143], v177 offset:16896
	ds_read_b64_tr_b16 v[136:137], v177 offset:20480
	ds_read_b64_tr_b16 v[138:139], v177 offset:20992
	ds_read_b64_tr_b16 v[132:133], v177 offset:24576
	ds_read_b64_tr_b16 v[134:135], v177 offset:25088
	ds_read_b64_tr_b16 v[128:129], v177 offset:28672
	ds_read_b64_tr_b16 v[130:131], v177 offset:29184
	s_waitcnt lgkmcnt(8)
	v_mfma_f32_32x32x16_bf16 v[80:95], v[190:193], v[124:127], v[80:95]
	s_cbranch_scc1 .LBB0_375
	v_add_u32_e32 v219, s69, v146
	v_add_u32_e32 v178, 0x18600, v219
	v_add_u32_e32 v180, 0x18680, v219
	v_add_u32_e32 v182, 0x18608, v219
	v_add_u32_e32 v184, 0x18688, v219
	v_add_u32_e32 v186, 0x18620, v219
	v_add_u32_e32 v188, 0x186a0, v219
	v_add_u32_e32 v190, 0x18628, v219
	v_add_u32_e32 v192, 0x186a8, v219
	v_add_u32_e32 v194, 0x18640, v219
	v_add_u32_e32 v196, 0x186c0, v219
	v_add_u32_e32 v198, 0x18648, v219
	v_add_u32_e32 v220, 0x186c8, v219
	v_add_u32_e32 v224, 0x18660, v219
	v_add_u32_e32 v226, 0x186e0, v219
	v_add_u32_e32 v222, 0x18668, v219
	ds_read2_b32 v[178:179], v178 offset1:1
	ds_read2_b32 v[180:181], v180 offset1:1
	ds_read2_b32 v[182:183], v182 offset1:1
	ds_read2_b32 v[184:185], v184 offset1:1
	ds_read2_b32 v[186:187], v186 offset1:1
	ds_read2_b32 v[188:189], v188 offset1:1
	ds_read2_b32 v[190:191], v190 offset1:1
	ds_read2_b32 v[192:193], v192 offset1:1
	ds_read2_b32 v[194:195], v194 offset1:1
	ds_read2_b32 v[196:197], v196 offset1:1
	ds_read2_b32 v[198:199], v198 offset1:1
	ds_read2_b32 v[220:221], v220 offset1:1
	ds_read2_b32 v[222:223], v222 offset1:1
	ds_read2_b32 v[224:225], v224 offset1:1
	v_add_u32_e32 v219, 0x186e8, v219
	ds_read2_b32 v[226:227], v226 offset1:1
	ds_read2_b32 v[228:229], v219 offset1:1
	s_waitcnt lgkmcnt(5)
	v_pk_add_f32 v[106:107], v[106:107], v[198:199]
	s_waitcnt lgkmcnt(3)
	v_pk_add_f32 v[110:111], v[110:111], v[222:223]
	s_waitcnt lgkmcnt(2)
	v_pk_add_f32 v[108:109], v[108:109], v[224:225]
	v_pk_add_f32 v[104:105], v[104:105], v[194:195]
	v_pk_add_f32 v[102:103], v[102:103], v[190:191]
	v_pk_add_f32 v[100:101], v[100:101], v[186:187]
	v_pk_add_f32 v[98:99], v[98:99], v[182:183]
	v_pk_add_f32 v[96:97], v[96:97], v[178:179]
	s_waitcnt lgkmcnt(0)
	v_pk_add_f32 v[94:95], v[94:95], v[228:229]
	v_pk_add_f32 v[92:93], v[92:93], v[226:227]
	v_pk_add_f32 v[90:91], v[90:91], v[220:221]
	v_pk_add_f32 v[88:89], v[88:89], v[196:197]
	v_pk_add_f32 v[86:87], v[86:87], v[192:193]
	v_pk_add_f32 v[84:85], v[84:85], v[188:189]
	v_pk_add_f32 v[82:83], v[82:83], v[184:185]
	v_pk_add_f32 v[80:81], v[80:81], v[180:181]
